# prompt attention queue: thread 0 claims the next item index (atomic) at the start of the current item, hiding the atomic round trip
# speedup vs baseline: 1.0033x; 1.0033x over previous
; __device__ void phaseB(const Params& p, unsigned char* smem, int pass, int item_lo, int item_hi) {
;     ...
;     for (int qi = 0; qi < 8; ++qi) {
;       const int queue = (xcd + qi) & 7;
;       for (;;) {
;         if (tid == 0) *s_item = atomicAdd(ctr + 1 + queue, 1);
.LBB0_337:
	s_mov_b32 s60, 0
	v_readlane_b32 s10, v254, 8
	s_add_i32 s1, s25, s10
	s_and_b32 s0, s24, 3
	s_and_b32 s6, s1, 7
	v_readlane_b32 s36, v255, 32
	s_lshl_b32 s0, s0, 11
	s_lshl_b32 s6, s6, 2
	v_readlane_b32 s46, v255, 42
	v_readlane_b32 s11, v254, 9
	v_readlane_b32 s37, v255, 33
	v_readlane_b32 s38, v255, 34
	v_readlane_b32 s39, v255, 35
	v_readlane_b32 s40, v255, 36
	v_readlane_b32 s41, v255, 37
	v_readlane_b32 s42, v255, 38
	v_readlane_b32 s43, v255, 39
	v_readlane_b32 s44, v255, 40
	v_readlane_b32 s45, v255, 41
	v_readlane_b32 s47, v255, 43
	v_readlane_b32 s48, v255, 44
	v_readlane_b32 s49, v255, 45
	v_readlane_b32 s50, v255, 46
	v_readlane_b32 s51, v255, 47
	s_add_u32 s10, s46, s6
	s_addc_u32 s11, s47, 0
	v_readlane_b32 s36, v255, 0
	v_readlane_b32 s48, v255, 12
	v_readlane_b32 s49, v255, 13
	s_lshl_b32 s6, s1, 1
	s_bfe_u32 s1, s1, 0x10002
	v_readlane_b32 s50, v255, 14
	v_readlane_b32 s51, v255, 15
	s_mov_b64 s[28:29], s[48:49]
	s_and_b32 s33, s6, 6
	s_lshl_b32 s34, s1, 14
	s_lshl_b32 s35, s1, 25
	s_mov_b64 s[30:31], s[50:51]
	v_readlane_b32 s37, v255, 1
	v_readlane_b32 s38, v255, 2
	s_add_u32 s36, s30, s35
	s_addc_u32 s37, s31, 0
	s_add_i32 s38, s0, 0
	s_add_i32 s38, s38, 0x105fc
	v_readlane_b32 s39, v255, 3
	v_readlane_b32 s40, v255, 4
	v_readlane_b32 s41, v255, 5
	v_readlane_b32 s42, v255, 6
	v_readlane_b32 s43, v255, 7
	v_readlane_b32 s44, v255, 8
	v_readlane_b32 s45, v255, 9
	v_readlane_b32 s46, v255, 10
	v_readlane_b32 s47, v255, 11
	s_branch .LBB0_340

; __device__ void phaseB(const Params& p, unsigned char* smem, int pass, int item_lo, int item_hi) {
;     ...
;         if (tid == 0) *s_item = atomicAdd(ctr + 1 + queue, 1);
;         __syncthreads();
;         const int j = *s_item;
.LBB0_340:
	s_and_saveexec_b64 s[0:1], s[4:5]
	s_cbranch_execz .LBB0_344
	s_mov_b64 s[14:15], exec
	v_mbcnt_lo_u32_b32 v0, s14, 0
	v_mbcnt_hi_u32_b32 v0, s15, v0
	v_cmp_eq_u32_e32 vcc, 0, v0
	s_and_saveexec_b64 s[12:13], vcc
	s_cbranch_execz .LBB0_343
	s_cmp_eq_u32 s60, 0
	s_cbranch_scc1 .Lq_fresh
	s_waitcnt vmcnt(0)
	v_mov_b32_e32 v1, v253
	s_branch .LBB0_343
.Lq_fresh:
	s_bcnt1_i32_b64 s6, s[14:15]
	v_mov_b32_e32 v1, s6
	global_atomic_add v1, v163, v1, s[10:11] offset:4 sc0

; __device__ void diff_item(const Params& p, unsigned char* smem, bool sample, int b, int h, int qb, float lam) {
;     ...
;   if (!sample) {
;     const int s = qb * 128 + g * 32 + r;
;     tok = b * SEQ + s;
;     qpos = s - r;
;     ntw = 2 * qb + (g >> 1) + 1;
;     ntb = 2 * qb + 2;
;     nvalid = 64;
;     active = true; valid = true;
;     kbase = p.Kall + (size_t)b * SEQ * 1024 + h * 128;
;     vtbase = p.VTp + (size_t)(b * 1024 + h * 128) * SEQ;
;     vld = SEQ;
;   } else {
;     tok = NPROMPT + b * 16 + (r < 16 ? r : 15);
;     qpos = 1024;
;     ntw = 17; ntb = 17; nvalid = 16;
;     active = (g == 0); valid = (r < 16);
;     kbase = p.Kall + ((size_t)NPROMPT + (size_t)b * SKV) * 1024 + h * 128;
;     vtbase = p.VTs + (size_t)(b * 1024 + h * 128) * SKV;
;     vld = SKV;
;   }
;   const u16* qptr = p.Qb + (size_t)tok * 1024 + h * 128 + c * 64 + hh * 8;
; __device__ void phaseB(const Params& p, unsigned char* smem, int pass, int item_lo, int item_hi) {
;     ...
;         if (tid == 0) *s_item = atomicAdd(ctr + 1 + queue, 1);
;         __syncthreads();
;         const int j = *s_item;
;         __syncthreads();
;         if (j >= 256) break;
;         const int bh = 2 * queue + (j & 1), qb = 127 - (j >> 1);
;         diff_item(p, smem, false, bh >> 3, bh & 7, qb, lam);
.LBB0_344:
	s_or_b64 exec, exec, s[0:1]
	s_waitcnt lgkmcnt(0)
	s_barrier
	ds_read_b32 v0, v172
	s_movk_i32 s0, 0xff
	s_waitcnt lgkmcnt(0)
	s_barrier
	v_cmp_lt_i32_e32 vcc, s0, v0
	v_readfirstlane_b32 s6, v0
	s_mov_b64 s[0:1], -1
	s_cbranch_vccnz .LBB0_339
	s_and_saveexec_b64 s[0:1], s[4:5]
	s_cbranch_execz .Lq_noclaim
	v_mov_b32_e32 v252, 1
	global_atomic_add v253, v163, v252, s[10:11] offset:4 sc0
.Lq_noclaim:
	s_mov_b64 exec, s[0:1]
	s_mov_b32 s60, 1
	v_mov_b32_e32 v175, v160
	s_ashr_i32 s62, s6, 1
	s_and_b32 s59, s6, 1
	v_readfirstlane_b32 s56, v175
	s_sub_i32 s0, 0x7f, s62
	s_bfe_u32 s39, s56, 0x20006
	s_or_b32 s57, s59, s33
	s_lshl_b32 s1, s0, 7
	s_lshl_b32 s6, s39, 5
	s_lshl_b32 s0, s0, 1
	v_and_b32_e32 v182, 31, v175
	s_ashr_i32 s64, s56, 8
	s_or_b32 s63, s6, s1
	s_or_b32 s58, s0, 1
	s_lshl_b32 s6, s57, 8
	v_or_b32_e32 v0, s34, v182
	s_add_u32 s14, s36, s6
	v_add_u32_e32 v0, s63, v0
	s_addc_u32 s15, s37, 0
	s_lshl_b32 s0, s57, 22
	s_or_b32 s0, s0, s35
	v_ashrrev_i32_e32 v1, 31, v0
	v_readlane_b32 s40, v255, 0
	s_add_u32 s20, s68, s0
	v_lshlrev_b64 v[164:165], 11, v[0:1]
	v_readlane_b32 s52, v255, 12
	v_readlane_b32 s53, v255, 13
	s_addc_u32 s21, s69, 0
	s_lshl_b32 s0, s64, 6
	v_lshl_add_u64 v[0:1], s[52:53], 0, v[164:165]
	v_bfe_u32 v174, v175, 5, 1
	v_lshl_add_u64 v[0:1], v[0:1], 0, s[6:7]
	s_ashr_i32 s1, s0, 31
	v_lshl_add_u64 v[0:1], s[0:1], 1, v[0:1]
	v_lshlrev_b32_e32 v162, 4, v174
	v_lshl_add_u64 v[2:3], v[0:1], 0, v[162:163]
	v_mov_b32_e32 v0, v160
	global_load_dwordx4 v[128:131], v[2:3], off
	global_load_dwordx4 v[132:135], v[2:3], off offset:32
	global_load_dwordx4 v[136:139], v[2:3], off offset:64
	global_load_dwordx4 v[140:143], v[2:3], off offset:96
	v_readfirstlane_b32 s1, v0
	s_movk_i32 s0, 0xffc0
	s_cmp_eq_u32 s64, 1
	v_mov_b32_e32 v1, s1
	v_bfi_b32 v1, s0, v1, v0
	s_cselect_b64 s[12:13], -1, 0
	s_cmp_lg_u32 s64, 1
	v_ashrrev_i32_e32 v2, 4, v1
	v_lshrrev_b32_e32 v3, 4, v1
	v_lshlrev_b32_e32 v4, 11, v1
	v_add_u32_e32 v1, 0x200, v1
	s_cselect_b64 s[16:17], -1, 0
	s_lshl_b32 s0, s1, 4
	v_xor_b32_e32 v5, v2, v0
	v_lshlrev_b32_e32 v6, 11, v2
	v_xor_b32_e32 v2, v3, v0
	v_ashrrev_i32_e32 v3, 4, v1
	s_and_b32 s0, s0, 0xfffffc00
	v_lshlrev_b32_e32 v7, 4, v5
	v_lshlrev_b32_e32 v2, 3, v2
	v_xor_b32_e32 v5, v3, v0
	s_add_i32 s6, s0, 0
	v_lshlrev_b32_e32 v3, 11, v3
	v_and_b32_e32 v2, 56, v2
	v_lshlrev_b32_e32 v5, 4, v5
	v_and_or_b32 v162, v7, s3, v6
	s_mov_b32 m0, s6
	v_lshlrev_b32_e32 v1, 11, v1
	v_and_or_b32 v4, v4, s22, v2
	v_and_or_b32 v170, v5, s3, v3
	v_and_or_b32 v1, v1, s22, v2
	v_lshlrev_b32_e32 v166, 1, v4
	v_lshlrev_b32_e32 v168, 1, v1
	v_mov_b32_e32 v167, v163
	v_mov_b32_e32 v169, v163
	v_lshl_add_u64 v[2:3], s[20:21], 0, v[166:167]
	v_lshl_add_u64 v[4:5], s[20:21], 0, v[168:169]
	v_lshl_add_u64 v[2:3], v[2:3], 0, s[8:9]
	v_lshl_add_u64 v[4:5], v[4:5], 0, s[8:9]
	v_mov_b32_e32 v171, v163
	v_readlane_b32 s41, v255, 1
	v_readlane_b32 s42, v255, 2
	v_readlane_b32 s43, v255, 3
	v_readlane_b32 s44, v255, 4
	v_readlane_b32 s45, v255, 5
	v_readlane_b32 s46, v255, 6
	v_readlane_b32 s47, v255, 7
	v_readlane_b32 s48, v255, 8
	v_readlane_b32 s49, v255, 9
	v_readlane_b32 s50, v255, 10
	v_readlane_b32 s51, v255, 11
	v_readlane_b32 s54, v255, 14
	v_readlane_b32 s55, v255, 15
	s_nop 0
	s_nop 0
	global_load_lds_dwordx4 v162, s[14:15]
	s_add_i32 m0, s6, 0x2000
	s_nop 0
	global_load_lds_dwordx4 v170, s[14:15]
	s_add_i32 m0, s6, 0x4000
	s_nop 0
	global_load_lds_dwordx4 v166, s[20:21]
	s_add_i32 m0, s6, 0x6000
	s_nop 0
	global_load_lds_dwordx4 v168, s[20:21]
	s_add_i32 m0, s6, 0x8000
	s_add_u32 s0, s14, 0x20000
	s_addc_u32 s1, s15, 0
	global_load_lds_dwordx4 v162, s[0:1]
	s_add_i32 m0, s6, 0xa000
	s_and_b64 vcc, exec, s[12:13]
	global_load_lds_dwordx4 v170, s[0:1]
	s_add_i32 m0, s6, 0xc000
	s_mov_b64 s[0:1], -1
	global_load_lds_dwordx4 v[2:3], off
	s_add_i32 m0, s6, 0xe000
	s_nop 0
	global_load_lds_dwordx4 v[4:5], off
	s_min_u32 s65, s58, 2
	s_add_i32 m0, s6, 0x10000
	s_lshl_b32 s0, s65, 17
	s_add_u32 s0, s14, s0
	s_addc_u32 s1, s15, 0
	v_lshl_add_u64 v[2:3], s[0:1], 0, v[162:163]
	s_lshl_b32 s65, s65, 7
	global_load_lds_dwordx4 v[2:3], off
	s_add_i32 m0, s6, 0x12000
	v_lshl_add_u64 v[2:3], s[0:1], 0, v[170:171]
	s_add_u32 s0, s20, s65
	s_addc_u32 s1, s21, 0
	global_load_lds_dwordx4 v[2:3], off
	v_lshl_add_u64 v[2:3], s[0:1], 0, v[166:167]
	s_add_i32 m0, s6, 0x14000
	s_nop 0
	global_load_lds_dwordx4 v[2:3], off
	v_lshl_add_u64 v[2:3], s[0:1], 0, v[168:169]
	s_add_i32 m0, s6, 0x16000
	s_mov_b64 s[0:1], 0
	global_load_lds_dwordx4 v[2:3], off
	s_waitcnt vmcnt(8)
